# norm phases (modes 1/2/3): 2-deep row prefetch with parity-selected register sets and counted latch wait
# baseline (speedup 1.0000x reference)
.LBB0_315:
	v_ashrrev_i32_e32 v0, 6, v141
	v_readlane_b32 s0, v255, 7
	s_nop 1
	v_add_u32_e32 v32, s0, v0
	s_mov_b32 s0, 0xc000
	v_cmp_gt_i32_e32 vcc, s0, v32
	s_and_saveexec_b64 s[12:13], vcc
	s_cbranch_execz .LBB0_328
	s_cmp_eq_u32 s56, 4
	s_cselect_b64 s[0:1], -1, 0
	s_or_b64 s[0:1], s[18:19], s[0:1]
	v_and_b32_e32 v1, 63, v141
	v_lshlrev_b32_e32 v15, 5, v1
	s_cmp_lg_u32 s56, 5
	v_cndmask_b32_e64 v14, 0.5, 1.0, s[0:1]
	global_load_dwordx4 v[2:5], v15, s[14:15] offset:16
	s_waitcnt lgkmcnt(0)
	global_load_dwordx4 v[6:9], v15, s[14:15]
	global_load_dwordx4 v[10:13], v15, s[14:15] offset:2064
	global_load_dwordx4 v[46:49], v15, s[14:15] offset:2048
	s_cselect_b64 s[14:15], -1, 0
	s_and_b64 s[0:1], s[0:1], exec
	s_cselect_b32 s92, 0xea80000, s87
	s_add_u32 s0, s88, s92
	v_ashrrev_i32_e32 v33, 31, v32
	s_addc_u32 s1, s89, 0
	v_lshlrev_b64 v[34:35], 11, v[32:33]
	v_lshl_add_u64 v[16:17], s[0:1], 0, v[34:35]
	v_readlane_b32 s0, v252, 55
	v_lshlrev_b32_e32 v128, 4, v1
	v_readlane_b32 s1, v252, 56
	v_lshl_add_u64 v[24:25], v[16:17], 0, v[128:129]
	v_lshlrev_b32_e32 v36, 2, v1
	v_lshl_add_u64 v[16:17], s[0:1], 0, v[34:35]
	v_lshl_add_u64 v[16:17], v[16:17], 0, v[128:129]
	global_load_dwordx4 v[20:23], v[16:17], off
	s_nop 0
	global_load_dwordx4 v[16:19], v[16:17], off offset:1024
	s_nop 0
	global_load_dwordx4 v[28:31], v[24:25], off
	s_nop 0
	global_load_dwordx4 v[24:27], v[24:25], off offset:1024
	v_readlane_b32 s0, v255, 8
	v_cmp_eq_u32_e64 s[38:39], 0, v1
	v_xor_b32_e32 v62, 0x80, v36
	v_add_u32_e32 v0, s0, v0
	v_ashrrev_i32_e32 v1, 31, v0
	v_xor_b32_e32 v63, 64, v36
	v_xor_b32_e32 v64, 32, v36
	v_xor_b32_e32 v65, 16, v36
	v_xor_b32_e32 v66, 8, v36
	v_xor_b32_e32 v67, 4, v36
	v_lshlrev_b64 v[36:37], 11, v[0:1]
	v_lshlrev_b64 v[0:1], 12, v[32:33]
	v_readlane_b32 s40, v252, 0
	v_or_b32_e32 v0, v0, v15
	v_readlane_b32 s46, v252, 6
	v_readlane_b32 s47, v252, 7
	v_or_b32_e32 v36, v36, v128
	v_or_b32_e32 v34, v34, v128
	v_lshl_add_u64 v[54:55], s[46:47], 0, v[0:1]
	v_mov_b64_e32 v[0:1], 0x2a50000
	v_lshl_add_u64 v[56:57], v[32:33], 2, v[0:1]
	v_lshl_add_u64 v[58:59], v[36:37], 0, s[92:93]
	s_mov_b64 s[30:31], 0
	v_readlane_b32 s41, v252, 1
	v_readlane_b32 s42, v252, 2
	v_readlane_b32 s43, v252, 3
	v_readlane_b32 s44, v252, 4
	v_readlane_b32 s45, v252, 5
	s_waitcnt vmcnt(0)
	v_pk_mul_f32 v[42:43], v[14:15], v[2:3] op_sel_hi:[0,1]
	v_pk_mul_f32 v[38:39], v[14:15], v[6:7] op_sel_hi:[0,1]
	v_pk_mul_f32 v[40:41], v[14:15], v[8:9] op_sel_hi:[0,1]
	v_pk_mul_f32 v[44:45], v[14:15], v[4:5] op_sel_hi:[0,1]
	v_pk_mul_f32 v[46:47], v[14:15], v[46:47] op_sel_hi:[0,1]
	v_pk_mul_f32 v[48:49], v[14:15], v[48:49] op_sel_hi:[0,1]
	v_pk_mul_f32 v[50:51], v[14:15], v[10:11] op_sel_hi:[0,1]
	v_pk_mul_f32 v[52:53], v[14:15], v[12:13] op_sel_hi:[0,1]
	v_lshl_add_u64 v[112:113], s[88:89], 0, v[36:37]
	v_lshl_add_u64 v[114:115], s[88:89], 0, v[58:59]
	v_add_co_u32_e32 v112, vcc, 0x8a80000, v112
	s_nop 0
	v_addc_co_u32_e32 v113, vcc, 0, v113, vcc
	global_load_dwordx4 v[0:3], v[114:115], off
	global_load_dwordx4 v[4:7], v[114:115], off offset:1024
	global_load_dwordx4 v[8:11], v[112:113], off
	global_load_dwordx4 v[12:15], v[112:113], off offset:1024
	s_branch .LBB0_318
.LBB0_317:
	v_readlane_b32 s4, v255, 19
	s_and_b64 s[0:1], exec, s[40:41]
	v_readlane_b32 s5, v255, 20
	s_or_b64 s[30:31], s[0:1], s[30:31]
	v_readlane_b32 s0, v255, 17
	v_lshl_add_u64 v[54:55], v[54:55], 0, s[4:5]
	v_readlane_b32 s4, v255, 21
	v_readlane_b32 s1, v255, 18
	v_readlane_b32 s5, v255, 22
	v_lshl_add_u64 v[36:37], v[36:37], 0, s[0:1]
	v_lshl_add_u64 v[56:57], v[56:57], 0, s[4:5]
	v_lshl_add_u64 v[34:35], v[34:35], 0, s[0:1]
	v_lshl_add_u64 v[58:59], v[58:59], 0, s[0:1]
	v_readfirstlane_b32 s18, v32
	s_add_i32 s19, s18, s24
	s_cmp_lt_i32 s19, 0xc000
	s_cbranch_scc0 .Lnm_tail
	s_and_b64 vcc, exec, s[14:15]
	s_cbranch_vccz .Lnm_w8
	s_and_b64 vcc, exec, s[8:9]
	s_cbranch_vccz .Lnm_w7
	s_waitcnt vmcnt(9)
	s_branch .Lnm_cp
.Lnm_w7:
	s_waitcnt vmcnt(7)
	s_branch .Lnm_cp
.Lnm_w8:
	s_waitcnt vmcnt(8)
	s_branch .Lnm_cp

.Lnm_cp:
	s_bitcmp1_b32 s18, 11
	s_cbranch_scc0 .Lnm_cpY
	v_mov_b64_e32 v[18:19], v[14:15]
	v_mov_b64_e32 v[16:17], v[12:13]
	v_mov_b64_e32 v[22:23], v[10:11]
	v_mov_b64_e32 v[20:21], v[8:9]
	v_mov_b64_e32 v[28:29], v[0:1]
	v_mov_b64_e32 v[30:31], v[2:3]
	v_mov_b64_e32 v[24:25], v[4:5]
	v_mov_b64_e32 v[26:27], v[6:7]
	s_branch .Lnm_cpd
.Lnm_cpY:
	v_mov_b64_e32 v[18:19], v[110:111]
	v_mov_b64_e32 v[16:17], v[108:109]
	v_mov_b64_e32 v[22:23], v[106:107]
	v_mov_b64_e32 v[20:21], v[104:105]
	v_mov_b64_e32 v[28:29], v[96:97]
	v_mov_b64_e32 v[30:31], v[98:99]
	v_mov_b64_e32 v[24:25], v[100:101]
	v_mov_b64_e32 v[26:27], v[102:103]
.Lnm_cpd:
	s_andn2_b64 exec, exec, s[30:31]
	s_cbranch_execz .LBB0_328
.LBB0_318:
	v_add_u32_e32 v32, s24, v32
	s_mov_b32 s0, 0xbfff
	v_cmp_lt_i32_e64 s[40:41], s0, v32
	v_readfirstlane_b32 s0, v32
	s_add_i32 s1, s0, s24
	s_cmp_lt_i32 s1, 0xc000
	s_cbranch_scc0 .LBB0_320
	v_readlane_b32 s4, v255, 17
	v_readlane_b32 s5, v255, 18
	s_nop 1
	v_lshl_add_u64 v[112:113], v[36:37], 0, s[4:5]
	v_lshl_add_u64 v[114:115], v[58:59], 0, s[4:5]
	v_lshl_add_u64 v[112:113], s[88:89], 0, v[112:113]
	v_lshl_add_u64 v[114:115], s[88:89], 0, v[114:115]
	v_add_co_u32_e32 v112, vcc, 0x8a80000, v112
	s_nop 0
	v_addc_co_u32_e32 v113, vcc, 0, v113, vcc
	s_bitcmp1_b32 s0, 11
	s_cbranch_scc0 .Lnm_pfX
	global_load_dwordx4 v[96:99], v[114:115], off
	global_load_dwordx4 v[100:103], v[114:115], off offset:1024
	global_load_dwordx4 v[104:107], v[112:113], off
	global_load_dwordx4 v[108:111], v[112:113], off offset:1024
	s_branch .LBB0_320
.Lnm_pfX:
	global_load_dwordx4 v[0:3], v[114:115], off
	global_load_dwordx4 v[4:7], v[114:115], off offset:1024
	global_load_dwordx4 v[8:11], v[112:113], off
	global_load_dwordx4 v[12:15], v[112:113], off offset:1024
.LBB0_320:
	v_lshlrev_b32_e32 v60, 16, v28
	v_and_b32_e32 v61, 0xffff0000, v28
	v_lshlrev_b32_e32 v68, 16, v29
	v_and_b32_e32 v69, 0xffff0000, v29
	v_lshlrev_b32_e32 v74, 16, v24
	v_and_b32_e32 v75, 0xffff0000, v24
	v_lshlrev_b32_e32 v76, 16, v25
	v_and_b32_e32 v77, 0xffff0000, v25
	v_pk_mul_f32 v[24:25], v[60:61], v[60:61]
	v_lshlrev_b32_e32 v78, 16, v26
	v_and_b32_e32 v79, 0xffff0000, v26
	v_lshlrev_b32_e32 v80, 16, v27
	v_and_b32_e32 v81, 0xffff0000, v27
	v_pk_mul_f32 v[26:27], v[68:69], v[68:69]
	v_add_f32_e32 v24, v24, v25
	v_lshlrev_b32_e32 v70, 16, v30
	v_and_b32_e32 v71, 0xffff0000, v30
	v_add_f32_e32 v24, v24, v26
	v_pk_mul_f32 v[28:29], v[70:71], v[70:71]
	v_add_f32_e32 v24, v27, v24
	v_lshlrev_b32_e32 v72, 16, v31
	v_and_b32_e32 v73, 0xffff0000, v31
	v_add_f32_e32 v24, v28, v24
	v_pk_mul_f32 v[30:31], v[72:73], v[72:73]
	v_add_f32_e32 v24, v29, v24
	v_add_f32_e32 v24, v30, v24
	v_pk_mul_f32 v[82:83], v[74:75], v[74:75]
	v_add_f32_e32 v24, v31, v24
	v_add_f32_e32 v24, v82, v24
	v_pk_mul_f32 v[84:85], v[76:77], v[76:77]
	v_add_f32_e32 v24, v83, v24
	v_add_f32_e32 v24, v84, v24
	v_pk_mul_f32 v[86:87], v[78:79], v[78:79]
	v_add_f32_e32 v24, v85, v24
	v_add_f32_e32 v24, v86, v24
	v_pk_mul_f32 v[88:89], v[80:81], v[80:81]
	v_add_f32_e32 v24, v87, v24
	v_add_f32_e32 v24, v88, v24
	v_add_f32_e32 v24, v89, v24
	ds_bpermute_b32 v25, v62, v24
	v_lshlrev_b32_e32 v82, 16, v16
	v_and_b32_e32 v83, 0xffff0000, v16
	v_lshlrev_b32_e32 v16, 16, v17
	v_and_b32_e32 v17, 0xffff0000, v17
	s_waitcnt lgkmcnt(0)
	v_add_f32_e32 v24, v24, v25
	ds_bpermute_b32 v25, v63, v24
	v_lshlrev_b32_e32 v84, 16, v18
	v_and_b32_e32 v85, 0xffff0000, v18
	v_lshlrev_b32_e32 v18, 16, v19
	v_and_b32_e32 v19, 0xffff0000, v19
	s_waitcnt lgkmcnt(0)
	v_add_f32_e32 v25, v24, v25
	ds_bpermute_b32 v26, v64, v25
	v_lshlrev_b32_e32 v24, 16, v20
	s_mov_b64 s[18:19], -1
	s_waitcnt lgkmcnt(0)
	v_add_f32_e32 v27, v25, v26
	ds_bpermute_b32 v28, v65, v27
	v_and_b32_e32 v25, 0xffff0000, v20
	v_lshlrev_b32_e32 v20, 16, v21
	v_and_b32_e32 v21, 0xffff0000, v21
	v_lshlrev_b32_e32 v26, 16, v22
	s_waitcnt lgkmcnt(0)
	v_add_f32_e32 v28, v27, v28
	ds_bpermute_b32 v29, v66, v28
	v_and_b32_e32 v27, 0xffff0000, v22
	v_lshlrev_b32_e32 v22, 16, v23
	v_and_b32_e32 v23, 0xffff0000, v23
	s_waitcnt lgkmcnt(0)
	v_add_f32_e32 v28, v28, v29
	ds_bpermute_b32 v29, v67, v28
	s_waitcnt lgkmcnt(0)
	v_add_f32_e32 v28, v28, v29
	v_fmamk_f32 v28, v28, 0x3a800000, v235
	v_mul_f32_e32 v29, 0x4b800000, v28
	v_cmp_gt_f32_e32 vcc, s86, v28
	s_nop 1
	v_cndmask_b32_e32 v28, v28, v29, vcc
	v_rsq_f32_e32 v28, v28
	s_nop 0
	v_mul_f32_e32 v29, 0x45800000, v28
	v_cndmask_b32_e32 v86, v28, v29, vcc
	v_pk_mul_f32 v[28:29], v[86:87], v[60:61] op_sel_hi:[0,1]
	v_pk_fma_f32 v[28:29], v[38:39], v[28:29], v[24:25]
	v_pk_mul_f32 v[24:25], v[86:87], v[68:69] op_sel_hi:[0,1]
	v_pk_fma_f32 v[30:31], v[40:41], v[24:25], v[20:21]
	v_pk_mul_f32 v[20:21], v[86:87], v[70:71] op_sel_hi:[0,1]
	v_pk_fma_f32 v[24:25], v[42:43], v[20:21], v[26:27]
	v_pk_mul_f32 v[20:21], v[86:87], v[72:73] op_sel_hi:[0,1]
	v_pk_fma_f32 v[26:27], v[44:45], v[20:21], v[22:23]
	v_pk_mul_f32 v[22:23], v[86:87], v[76:77] op_sel_hi:[0,1]
	v_pk_mul_f32 v[20:21], v[86:87], v[74:75] op_sel_hi:[0,1]
	v_pk_fma_f32 v[22:23], v[48:49], v[22:23], v[16:17]
	v_pk_mul_f32 v[16:17], v[86:87], v[78:79] op_sel_hi:[0,1]
	v_pk_mul_f32 v[60:61], v[86:87], v[80:81] op_sel_hi:[0,1]
	v_pk_fma_f32 v[20:21], v[46:47], v[20:21], v[82:83]
	v_pk_fma_f32 v[16:17], v[50:51], v[16:17], v[84:85]
	v_pk_fma_f32 v[18:19], v[52:53], v[60:61], v[18:19]
	s_andn2_b64 vcc, exec, s[14:15]
	s_cbranch_vccnz .LBB0_326
	v_pk_mul_f32 v[60:61], v[28:29], v[28:29]
	v_pk_mul_f32 v[68:69], v[30:31], v[30:31]
	v_add_f32_e32 v33, v60, v61
	v_add_f32_e32 v33, v68, v33
	v_pk_mul_f32 v[70:71], v[24:25], v[24:25]
	v_add_f32_e32 v33, v69, v33
	v_add_f32_e32 v33, v70, v33
	v_pk_mul_f32 v[72:73], v[26:27], v[26:27]
	v_add_f32_e32 v33, v71, v33
	v_add_f32_e32 v33, v72, v33
	v_pk_mul_f32 v[74:75], v[20:21], v[20:21]
	v_add_f32_e32 v33, v73, v33
	v_add_f32_e32 v33, v74, v33
	v_pk_mul_f32 v[76:77], v[22:23], v[22:23]
	v_add_f32_e32 v33, v75, v33
	v_add_f32_e32 v33, v76, v33
	v_pk_mul_f32 v[78:79], v[16:17], v[16:17]
	v_add_f32_e32 v33, v77, v33
	v_add_f32_e32 v33, v78, v33
	v_pk_mul_f32 v[80:81], v[18:19], v[18:19]
	v_add_f32_e32 v33, v79, v33
	v_add_f32_e32 v33, v80, v33
	v_add_f32_e32 v33, v81, v33
	ds_bpermute_b32 v60, v62, v33
	s_mov_b32 s0, 0x8a80000
	v_cvt_pk_bf16_f32 v69, v30, v31
	v_cvt_pk_bf16_f32 v70, v24, v25
	v_cvt_pk_bf16_f32 v71, v26, v27
	s_waitcnt lgkmcnt(0)
	v_add_f32_e32 v33, v33, v60
	ds_bpermute_b32 v60, v63, v33
	s_waitcnt lgkmcnt(0)
	v_add_f32_e32 v33, v33, v60
	ds_bpermute_b32 v68, v64, v33
	v_lshl_add_u64 v[60:61], s[88:89], 0, v[34:35]
	s_waitcnt lgkmcnt(0)
	v_add_f32_e32 v33, v33, v68
	ds_bpermute_b32 v72, v65, v33
	v_cvt_pk_bf16_f32 v68, v28, v29
	s_waitcnt lgkmcnt(0)
	v_add_f32_e32 v33, v33, v72
	ds_bpermute_b32 v74, v66, v33
	v_add_co_u32_e32 v72, vcc, s0, v60
	s_waitcnt lgkmcnt(0)
	v_add_f32_e32 v33, v33, v74
	ds_bpermute_b32 v74, v67, v33
	v_addc_co_u32_e32 v73, vcc, 0, v61, vcc
	global_store_dwordx4 v[72:73], v[68:71], off
	s_waitcnt lgkmcnt(0)
	v_add_f32_e32 v33, v33, v74
	v_cvt_pk_bf16_f32 v68, v20, v21
	v_cvt_pk_bf16_f32 v69, v22, v23
	v_cvt_pk_bf16_f32 v70, v16, v17
	v_cvt_pk_bf16_f32 v71, v18, v19
	global_store_dwordx4 v[72:73], v[68:71], off offset:1024
	s_and_saveexec_b64 s[18:19], s[38:39]
	s_cbranch_execz .LBB0_323
	v_lshl_add_u64 v[68:69], s[88:89], 0, v[56:57]
	global_store_dword v[68:69], v33, off
